# retention drain loop: remaining six loads of a batch no longer wait for the previous batch's store acknowledgements
# speedup vs baseline: 1.0275x; 1.0041x over previous
.LBB0_2537:
	s_add_i32 s58, s43, 1
	s_min_i32 s12, s58, s18
	s_ashr_i32 s4, s12, 6
	s_mul_i32 s4, s4, s96
	s_add_i32 s4, s4, s2
	s_ashr_i32 s5, s4, 31
	s_lshl_b64 s[4:5], s[4:5], 8
	s_and_b32 s12, s12, 63
	s_add_i32 s57, s43, 2
	s_or_b32 s4, s4, s12
	s_min_i32 s12, s57, s18
	v_or_b32_e32 v32, s4, v62
	s_ashr_i32 s4, s12, 6
	s_mul_i32 s4, s4, s96
	s_add_i32 s4, s4, s2
	v_mov_b32_e32 v33, s5
	s_ashr_i32 s5, s4, 31
	s_lshl_b64 s[4:5], s[4:5], 8
	s_and_b32 s12, s12, 63
	s_add_i32 s56, s43, 3
	s_or_b32 s4, s4, s12
	s_min_i32 s12, s56, s18
	v_or_b32_e32 v34, s4, v62
	s_ashr_i32 s4, s12, 6
	s_mul_i32 s4, s4, s96
	s_add_i32 s4, s4, s2
	v_mov_b32_e32 v35, s5
	s_ashr_i32 s5, s4, 31
	v_lshlrev_b64 v[32:33], 11, v[32:33]
	s_lshl_b64 s[4:5], s[4:5], 8
	s_and_b32 s12, s12, 63
	s_add_i32 s39, s43, 4
	v_lshl_add_u64 v[32:33], v[64:65], 0, v[32:33]
	v_lshlrev_b64 v[34:35], 11, v[34:35]
	s_or_b32 s4, s4, s12
	s_min_i32 s12, s39, s18
	v_lshl_add_u64 v[34:35], v[64:65], 0, v[34:35]
	global_load_dwordx4 v[56:59], v[32:33], off nt
	global_load_dwordx4 v[52:55], v[34:35], off nt
	v_or_b32_e32 v32, s4, v62
	s_ashr_i32 s4, s12, 6
	s_mul_i32 s4, s4, s96
	s_add_i32 s4, s4, s2
	v_mov_b32_e32 v33, s5
	s_ashr_i32 s5, s4, 31
	s_lshl_b64 s[4:5], s[4:5], 8
	s_and_b32 s12, s12, 63
	s_add_i32 s38, s43, 5
	s_or_b32 s4, s4, s12
	s_min_i32 s12, s38, s18
	v_or_b32_e32 v34, s4, v62
	s_ashr_i32 s4, s12, 6
	s_mul_i32 s4, s4, s96
	s_add_i32 s4, s4, s2
	v_mov_b32_e32 v35, s5
	s_ashr_i32 s5, s4, 31
	s_lshl_b64 s[4:5], s[4:5], 8
	s_and_b32 s12, s12, 63
	s_add_i32 s19, s43, 7
	s_or_b32 s4, s4, s12
	s_min_i32 s12, s19, s18
	s_waitcnt vmcnt(11)
	v_or_b32_e32 v36, s4, v62
	s_ashr_i32 s4, s12, 6
	s_mul_i32 s4, s4, s96
	s_add_i32 s4, s4, s2
	v_mov_b32_e32 v37, s5
	s_ashr_i32 s5, s4, 31
	v_lshlrev_b64 v[32:33], 11, v[32:33]
	s_lshl_b64 s[4:5], s[4:5], 8
	s_and_b32 s12, s12, 63
	v_lshl_add_u64 v[32:33], v[64:65], 0, v[32:33]
	v_lshlrev_b64 v[34:35], 11, v[34:35]
	s_or_b32 s4, s4, s12
	s_min_i32 s12, s43, s18
	v_lshl_add_u64 v[34:35], v[64:65], 0, v[34:35]
	global_load_dwordx4 v[48:51], v[32:33], off nt
	global_load_dwordx4 v[44:47], v[34:35], off nt
	v_or_b32_e32 v32, s4, v62
	s_ashr_i32 s4, s12, 6
	s_mul_i32 s4, s4, s96
	s_add_i32 s4, s4, s2
	v_mov_b32_e32 v33, s5
	s_ashr_i32 s5, s4, 31
	s_lshl_b64 s[4:5], s[4:5], 8
	s_and_b32 s12, s12, 63
	s_add_i32 s27, s43, 6
	s_or_b32 s4, s4, s12
	s_min_i32 s12, s27, s18
	v_or_b32_e32 v34, s4, v62
	s_ashr_i32 s4, s12, 6
	s_mul_i32 s4, s4, s96
	s_add_i32 s4, s4, s2
	v_lshlrev_b64 v[32:33], 11, v[32:33]
	v_mov_b32_e32 v35, s5
	s_ashr_i32 s5, s4, 31
	v_lshl_add_u64 v[32:33], v[64:65], 0, v[32:33]
	v_lshlrev_b64 v[34:35], 11, v[34:35]
	s_lshl_b64 s[4:5], s[4:5], 8
	s_and_b32 s12, s12, 63
	v_lshl_add_u64 v[38:39], v[64:65], 0, v[34:35]
	global_load_dwordx4 v[32:35], v[32:33], off nt
	s_nop 0
	global_load_dwordx4 v[66:69], v[38:39], off nt
	s_or_b32 s4, s4, s12
	v_mov_b32_e32 v39, s5
	v_or_b32_e32 v38, s4, v62
	v_lshlrev_b64 v[36:37], 11, v[36:37]
	v_lshlrev_b64 v[38:39], 11, v[38:39]
	v_lshl_add_u64 v[36:37], v[64:65], 0, v[36:37]
	v_lshl_add_u64 v[38:39], v[64:65], 0, v[38:39]
	global_load_dwordx4 v[40:43], v[36:37], off nt
	s_nop 0
	global_load_dwordx4 v[36:39], v[38:39], off nt
	s_ashr_i32 s5, s43, 6
	s_mul_i32 s4, s5, s96
	s_add_i32 s4, s4, s2
	s_lshl_b32 s5, s5, 12
	s_and_b32 s60, s43, 63
	s_add_i32 s5, s5, 0
	s_and_b32 s59, s4, 3
	v_or_b32_e32 v63, s60, v62
	s_add_i32 s5, s5, 0x1d800
	s_add_i32 s12, s59, 5
	v_lshl_add_u32 v70, v63, 2, s5
	v_cvt_f32_ubyte0_e32 v71, s12
	v_exp_f32_e64 v76, -v71
	ds_read2st64_b32 v[74:75], v70 offset1:4
	v_lshl_add_u32 v70, v60, 2, s5
	ds_read_b128 v[70:73], v70 offset:2048
	s_ashr_i32 s5, s4, 31
	v_sub_f32_e32 v76, 1.0, v76
	s_lshl_b64 s[12:13], s[4:5], 19
	s_add_u32 s12, s14, s12
	s_addc_u32 s13, s6, s13
	s_cmp_lg_u32 s60, 63
	s_waitcnt vmcnt(2)
	v_pk_mul_f32 v[68:69], v[76:77], v[68:69] op_sel_hi:[0,1]
	v_pk_mul_f32 v[66:67], v[76:77], v[66:67] op_sel_hi:[0,1]
	s_waitcnt lgkmcnt(1)
	v_mov_b32_e32 v76, v75
	s_waitcnt lgkmcnt(0)
	v_pk_fma_f32 v[66:67], v[70:71], v[76:77], v[66:67] op_sel_hi:[1,0,1]
	v_lshlrev_b32_e32 v70, 11, v63
	v_mov_b32_e32 v71, v81
	v_pk_fma_f32 v[68:69], v[72:73], v[76:77], v[68:69] op_sel_hi:[1,0,1]
	v_lshl_add_u64 v[70:71], s[12:13], 0, v[70:71]
	v_lshl_add_u64 v[70:71], v[60:61], 2, v[70:71]
	v_pk_fma_f32 v[218:219], v[74:75], v[68:69], v[218:219] op_sel_hi:[0,1,1]
	v_pk_fma_f32 v[220:221], v[74:75], v[66:67], v[220:221] op_sel_hi:[0,1,1]
	global_store_dwordx4 v[70:71], v[66:69], off nt
	s_cbranch_scc1 .LBB0_2541
	v_add_f32_dpp v63, v220, v220 quad_perm:[1,0,3,2] row_mask:0xf bank_mask:0xf bound_ctrl:1
	v_mov_b32_e32 v66, 0
	v_add_f32_dpp v67, v221, v221 quad_perm:[1,0,3,2] row_mask:0xf bank_mask:0xf bound_ctrl:1
	v_mov_b32_e32 v68, 0
	v_add_f32_dpp v69, v218, v218 quad_perm:[1,0,3,2] row_mask:0xf bank_mask:0xf bound_ctrl:1
	v_mov_b32_e32 v70, 0
	v_add_f32_dpp v71, v219, v219 quad_perm:[1,0,3,2] row_mask:0xf bank_mask:0xf bound_ctrl:1
	v_mov_b32_e32 v72, 0
	v_mov_b32_dpp v66, v63 quad_perm:[2,3,0,1] row_mask:0xf bank_mask:0xf
	v_mov_b32_dpp v68, v67 quad_perm:[2,3,0,1] row_mask:0xf bank_mask:0xf
	v_mov_b32_dpp v70, v69 quad_perm:[2,3,0,1] row_mask:0xf bank_mask:0xf
	v_mov_b32_dpp v72, v71 quad_perm:[2,3,0,1] row_mask:0xf bank_mask:0xf
	s_and_saveexec_b64 s[12:13], s[54:55]
	s_cbranch_execz .LBB0_2540
	s_ashr_i32 s4, s4, 2
	s_ashr_i32 s5, s4, 31
	s_lshl_b64 s[4:5], s[4:5], 12
	s_add_u32 s4, s86, s4
	s_addc_u32 s5, s87, s5
	s_lshl_b32 s59, s59, 10
	s_add_u32 s4, s4, s59
	v_add_f32_e32 v69, v69, v70
	v_add_f32_e32 v67, v67, v68
	s_addc_u32 s5, s5, 0
	v_add_f32_e32 v71, v71, v72
	v_add_f32_e32 v63, v63, v66
	v_cvt_pk_bf16_f32 v66, v63, v67
	v_cvt_pk_bf16_f32 v67, v69, v71
	v_lshl_add_u64 v[68:69], v[60:61], 1, s[4:5]
	v_add_co_u32_e32 v68, vcc, 0x4080000, v68
	s_nop 1
	v_addc_co_u32_e32 v69, vcc, 0, v69, vcc
	global_store_dwordx2 v[68:69], v[66:67], off
